# row-sum chains: the zero-initialised first add folded into the second (2 VALU fewer per iteration), on top of the slot-specialised loop
# speedup vs baseline: 1.0150x; 1.0082x over previous
; #define SBAR() __builtin_amdgcn_sched_barrier(0)
; #define PK4(P, BASE, OUT) do { u32x4 w = {cvtpk(P[BASE + 0], P[BASE + 1]), cvtpk(P[BASE + 2], P[BASE + 3]), cvtpk(P[BASE + 4], P[BASE + 5]), cvtpk(P[BASE + 6], P[BASE + 7])}; \
;     OUT = *reinterpret_cast<bf16x8*>(&w); } while (0)
; __device__ __forceinline__ void finishSM(f32x16& p0, f32x16& p1, float alpha, float& l_reg, bf16x8& pa0, bf16x8& pa1, bf16x8& pa2, bf16x8& pa3) {
;   for (int r = 0; r < 16; ++r) p1[r] = __builtin_amdgcn_exp2f(p1[r]);
;   float ps = 0; for (int r = 0; r < 16; ++r) ps += p0[r]; for (int r = 0; r < 16; ++r) ps += p1[r];
;   asm volatile("" : "+v"(ps));
;   l_reg = l_reg * alpha + ps;
;     ...
;   PK4(p0, 0, pa0); PK4(p0, 8, pa1); PK4(p1, 0, pa2); PK4(p1, 8, pa3);
;     ...
; }
; template <typename TQ> ...
;     ...
;   for (int j = 1; j + 1 < NT; j += 2) {
;     SBAR(); qkt(pB0, pB1, (const bf16*)(K_lds + (j & 3) * (int)SHM_K), qr, r32, hi);
;     finishSM(pA0, pA1, alA, l_reg, pa0, pa1, pa2, pa3); SBAR();
;     DMA_TILE(j + 2, (j + 2) & 3); SBAR();
;     pv_d0(o, vb0 + ((j - 1) & 3) * (int)SHM_V, pa0, pa1, pa2, pa3); partialSM<true>(pB0, pB1, m_reg, mnB, alB);
.LBB0_461:
	s_bitcmp1_b32 s73, 1
	s_cbranch_scc1 .Lat461_b_in
	s_mov_b32 s40, s33
	s_addk_i32 s33, 0xc000
	s_and_b32 s42, s33, 0xc000
	s_add_i32 s33, s57, s42
	ds_read_b128 v[80:83], v178 offset:16384
	ds_read_b128 v[84:87], v178 offset:24576
	ds_read_b128 v[198:201], v179 offset:16384
	ds_read_b128 v[202:205], v179 offset:24576
	s_waitcnt lgkmcnt(3)
	v_mfma_f32_32x32x16_bf16 v[96:111], v[80:83], v[136:139], 0
	v_exp_f32_e32 v238, v64
	v_add_f32_e32 v64, v197, v196
	v_add_f32_e32 v64, v193, v64
	v_add_f32_e32 v64, v195, v64
	s_waitcnt lgkmcnt(2)
	v_mfma_f32_32x32x16_bf16 v[80:95], v[84:87], v[136:139], 0
	v_add_f32_e32 v64, v191, v64
	v_add_f32_e32 v64, v194, v64
	v_add_f32_e32 v64, v190, v64
	v_add_f32_e32 v64, v192, v64
	v_add_f32_e32 v64, v169, v64
	v_add_f32_e32 v64, v171, v64
	s_waitcnt lgkmcnt(1)
	v_mfma_f32_32x32x16_bf16 v[96:111], v[198:201], v[140:143], v[96:111]
	v_add_f32_e32 v64, v167, v64
	v_add_f32_e32 v64, v170, v64
	v_add_f32_e32 v64, v165, v64
	v_add_f32_e32 v64, v168, v64
	v_add_f32_e32 v64, v164, v64
	v_add_f32_e32 v64, v166, v64
	v_exp_f32_e32 v239, v68
	s_waitcnt lgkmcnt(0)
	v_mfma_f32_32x32x16_bf16 v[80:95], v[202:205], v[140:143], v[80:95]
	ds_read_b128 v[198:201], v180 offset:16384
	ds_read_b128 v[202:205], v180 offset:24576
	v_add_f32_e32 v64, v238, v64
	v_exp_f32_e32 v240, v69
	v_exp_f32_e32 v241, v70
	v_exp_f32_e32 v242, v71
	s_waitcnt lgkmcnt(1)
	v_mfma_f32_32x32x16_bf16 v[96:111], v[198:201], v[132:135], v[96:111]
	ds_read_b128 v[198:201], v181 offset:16384
	ds_read_b128 v[206:209], v181 offset:24576
	ds_read_b128 v[210:213], v182 offset:16384
	ds_read_b128 v[214:217], v182 offset:24576
	ds_read_b128 v[218:221], v183 offset:16384
	ds_read_b128 v[222:225], v183 offset:24576
	v_exp_f32_e32 v243, v76
	v_exp_f32_e32 v244, v77
	v_exp_f32_e32 v245, v78
	v_exp_f32_e32 v79, v79
	s_waitcnt lgkmcnt(6)
	v_mfma_f32_32x32x16_bf16 v[80:95], v[202:205], v[132:135], v[80:95]
	ds_read_b128 v[202:205], v184 offset:16384
	ds_read_b128 v[226:229], v184 offset:24576
	ds_read_b128 v[230:233], v185 offset:16384
	ds_read_b128 v[234:237], v185 offset:24576
	s_waitcnt lgkmcnt(9)
	v_mfma_f32_32x32x16_bf16 v[96:111], v[198:201], v[128:131], v[96:111]
	v_exp_f32_e32 v199, v65
	v_exp_f32_e32 v200, v66
	v_exp_f32_e32 v201, v67
	v_add_f32_e32 v64, v199, v64
	v_add_f32_e32 v64, v200, v64
	v_add_f32_e32 v64, v201, v64
	s_waitcnt lgkmcnt(8)
	v_mfma_f32_32x32x16_bf16 v[80:95], v[206:209], v[128:131], v[80:95]
	v_exp_f32_e32 v206, v72
	v_add_f32_e32 v64, v239, v64
	v_exp_f32_e32 v207, v73
	v_add_f32_e32 v64, v240, v64
	v_exp_f32_e32 v208, v74
	v_add_f32_e32 v64, v241, v64
	v_exp_f32_e32 v209, v75
	s_waitcnt lgkmcnt(7)
	v_mfma_f32_32x32x16_bf16 v[96:111], v[210:213], v[124:127], v[96:111]
	v_add_f32_e32 v64, v242, v64
	v_add_f32_e32 v64, v206, v64
	v_add_f32_e32 v64, v207, v64
	v_add_f32_e32 v64, v208, v64
	v_add_f32_e32 v64, v209, v64
	v_add_f32_e32 v64, v243, v64
	v_add_f32_e32 v64, v244, v64
	s_waitcnt lgkmcnt(6)
	v_mfma_f32_32x32x16_bf16 v[80:95], v[214:217], v[124:127], v[80:95]
	v_add_f32_e32 v64, v245, v64
	v_add_f32_e32 v198, v79, v64
	v_cvt_pk_bf16_f32 v64, v196, v197
	v_cvt_pk_bf16_f32 v65, v193, v195
	v_cvt_pk_bf16_f32 v66, v191, v194
	v_cvt_pk_bf16_f32 v67, v190, v192
	s_waitcnt lgkmcnt(5)
	v_mfma_f32_32x32x16_bf16 v[96:111], v[218:221], v[120:123], v[96:111]
	v_cvt_pk_bf16_f32 v68, v169, v171
	v_cvt_pk_bf16_f32 v69, v167, v170
	v_cvt_pk_bf16_f32 v70, v165, v168
	v_cvt_pk_bf16_f32 v71, v164, v166
	v_cvt_pk_bf16_f32 v72, v238, v199
	v_cvt_pk_bf16_f32 v73, v200, v201
	v_cvt_pk_bf16_f32 v74, v239, v240
	s_waitcnt lgkmcnt(4)
	v_mfma_f32_32x32x16_bf16 v[80:95], v[222:225], v[120:123], v[80:95]
	v_cvt_pk_bf16_f32 v75, v241, v242
	v_cvt_pk_bf16_f32 v76, v206, v207
	v_cvt_pk_bf16_f32 v77, v208, v209
	v_cvt_pk_bf16_f32 v78, v243, v244
	v_cvt_pk_bf16_f32 v79, v245, v79
	s_waitcnt lgkmcnt(3)
	v_mfma_f32_32x32x16_bf16 v[96:111], v[202:205], v[116:119], v[96:111]
	s_add_i32 s33, s40, 0x8000
	s_and_b32 s43, s33, 0xc000
	ds_read_b64_tr_b16 v[190:191], v176
	ds_read_b64_tr_b16 v[192:193], v176 offset:2048
	ds_read_b64_tr_b16 v[194:195], v176 offset:4096
	ds_read_b64_tr_b16 v[196:197], v176 offset:6144
	s_waitcnt lgkmcnt(6)
	v_mfma_f32_32x32x16_bf16 v[80:95], v[226:229], v[116:119], v[80:95]
	ds_read_b64_tr_b16 v[200:201], v176 offset:8192
	ds_read_b64_tr_b16 v[202:203], v176 offset:10240
	ds_read_b64_tr_b16 v[204:205], v176 offset:12288
	ds_read_b64_tr_b16 v[206:207], v176 offset:14336
	s_add_i32 s74, s40, 0x4000
	s_and_b32 s74, s74, 0xc000
	s_add_u32 s98, s38, s22
	s_addc_u32 s99, s39, s23
	s_add_i32 s41, s67, s74
	s_add_u32 s100, s38, s24
	s_addc_u32 s101, s39, s25
	s_mov_b32 m0, s41
	s_add_i32 s74, s72, s74
	global_load_lds_dwordx4 v156, s[98:99]
	s_waitcnt lgkmcnt(9)
	v_mfma_f32_32x32x16_bf16 v[96:111], v[230:233], v[112:115], v[96:111]
	s_add_i32 m0, s41, 0x2000
	s_nop 0
	global_load_lds_dwordx4 v158, s[98:99]
	s_mov_b32 m0, s74
	s_nop 0
	global_load_lds_dwordx4 v162, s[100:101]
	s_waitcnt lgkmcnt(8)
	v_mfma_f32_32x32x16_bf16 v[80:95], v[234:237], v[112:115], v[80:95]
	s_add_i32 m0, s74, 0x2000
	s_nop 0
	global_load_lds_dwordx4 v160, s[100:101]
	s_nop 0
	s_waitcnt lgkmcnt(6)
	v_mfma_f32_32x32x16_bf16 v[48:63], v[64:67], v[190:193], v[48:63]
	v_exp_f32_e32 v232, v96
	ds_read_b64_tr_b16 v[190:191], v176 offset:512
	ds_read_b64_tr_b16 v[192:193], v176 offset:2560
	s_waitcnt lgkmcnt(6)
	v_mfma_f32_32x32x16_bf16 v[48:63], v[68:71], v[194:197], v[48:63]
	v_exp_f32_e32 v233, v97
	ds_read_b64_tr_b16 v[194:195], v176 offset:4608
	ds_read_b64_tr_b16 v[196:197], v176 offset:6656
	s_waitcnt lgkmcnt(6)
; #define SBAR() __builtin_amdgcn_sched_barrier(0)
; #define PUBLISH(n) do { asm volatile("s_waitcnt vmcnt(" #n ")" ::: "memory"); asm volatile("s_waitcnt lgkmcnt(0)" ::: "memory"); __builtin_amdgcn_s_barrier(); SBAR(); } while (0)
; template <typename TQ> ...
;     ...
;     pv_d0(o, vb0 + ((j - 1) & 3) * (int)SHM_V, pa0, pa1, pa2, pa3); partialSM<true>(pB0, pB1, m_reg, mnB, alB);
;     PUBLISH(4);
;     SBAR(); qkt(pA0, pA1, (const bf16*)(K_lds + ((j + 1) & 3) * (int)SHM_K), qr, r32, hi);
;     finishSM(pB0, pB1, alB, l_reg, pa0, pa1, pa2, pa3); SBAR();
;     if (j + 3 < NT) { DMA_TILE(j + 3, (j + 3) & 3); } SBAR();
	v_mfma_f32_32x32x16_bf16 v[48:63], v[72:75], v[200:203], v[48:63]
	v_exp_f32_e32 v234, v98
	ds_read_b64_tr_b16 v[200:201], v176 offset:8704
	ds_read_b64_tr_b16 v[202:203], v176 offset:10752
	ds_read_b64_tr_b16 v[208:209], v176 offset:12800
	ds_read_b64_tr_b16 v[210:211], v176 offset:14848
	s_waitcnt lgkmcnt(8)
	v_mfma_f32_32x32x16_bf16 v[48:63], v[76:79], v[204:207], v[48:63]
	v_exp_f32_e32 v235, v99
	s_waitcnt lgkmcnt(6)
	v_mfma_f32_32x32x16_bf16 v[32:47], v[64:67], v[190:193], v[32:47]
	v_exp_f32_e32 v236, v100
	ds_read_b64_tr_b16 v[190:191], v176 offset:1024
	ds_read_b64_tr_b16 v[192:193], v176 offset:3072
	s_waitcnt lgkmcnt(6)
	v_mfma_f32_32x32x16_bf16 v[32:47], v[68:71], v[194:197], v[32:47]
	v_exp_f32_e32 v237, v101
	ds_read_b64_tr_b16 v[194:195], v176 offset:5120
	ds_read_b64_tr_b16 v[196:197], v176 offset:7168
	s_waitcnt lgkmcnt(6)
	v_mfma_f32_32x32x16_bf16 v[32:47], v[72:75], v[200:203], v[32:47]
	v_exp_f32_e32 v238, v102
	ds_read_b64_tr_b16 v[200:201], v176 offset:9216
	ds_read_b64_tr_b16 v[202:203], v176 offset:11264
	ds_read_b64_tr_b16 v[204:205], v176 offset:13312
	ds_read_b64_tr_b16 v[206:207], v176 offset:15360
	s_waitcnt lgkmcnt(8)
	v_mfma_f32_32x32x16_bf16 v[32:47], v[76:79], v[208:211], v[32:47]
	v_exp_f32_e32 v239, v103
	v_exp_f32_e32 v240, v104
	s_waitcnt lgkmcnt(6)
	v_mfma_f32_32x32x16_bf16 v[16:31], v[64:67], v[190:193], v[16:31]
	v_exp_f32_e32 v241, v105
	ds_read_b64_tr_b16 v[190:191], v176 offset:1536
	ds_read_b64_tr_b16 v[192:193], v176 offset:3584
	s_waitcnt lgkmcnt(6)
	v_mfma_f32_32x32x16_bf16 v[16:31], v[68:71], v[194:197], v[16:31]
	v_exp_f32_e32 v242, v106
	ds_read_b64_tr_b16 v[194:195], v176 offset:5632
	ds_read_b64_tr_b16 v[196:197], v176 offset:7680
	s_waitcnt lgkmcnt(6)
	v_mfma_f32_32x32x16_bf16 v[16:31], v[72:75], v[200:203], v[16:31]
	v_exp_f32_e32 v243, v107
	ds_read_b64_tr_b16 v[200:201], v176 offset:9728
	ds_read_b64_tr_b16 v[202:203], v176 offset:11776
	ds_read_b64_tr_b16 v[208:209], v176 offset:13824
	ds_read_b64_tr_b16 v[210:211], v176 offset:15872
	s_waitcnt lgkmcnt(8)
	v_mfma_f32_32x32x16_bf16 v[16:31], v[76:79], v[204:207], v[16:31]
	v_exp_f32_e32 v244, v108
	s_waitcnt lgkmcnt(6)
	v_mfma_f32_32x32x16_bf16 v[0:15], v[64:67], v[190:193], v[0:15]
	v_exp_f32_e32 v245, v109
	s_waitcnt lgkmcnt(4)
	v_mfma_f32_32x32x16_bf16 v[0:15], v[68:71], v[194:197], v[0:15]
	v_exp_f32_e32 v246, v110
	s_waitcnt lgkmcnt(2)
	v_mfma_f32_32x32x16_bf16 v[0:15], v[72:75], v[200:203], v[0:15]
	v_exp_f32_e32 v247, v111
	s_waitcnt vmcnt(4)
	s_waitcnt lgkmcnt(0)
	s_barrier
	v_mfma_f32_32x32x16_bf16 v[0:15], v[76:79], v[208:211], v[0:15]
	s_and_b32 s40, s40, 0xc000
	s_add_i32 s40, s57, s40
	ds_read_b128 v[64:67], v178 offset:32768
	ds_read_b128 v[68:71], v178 offset:40960
	ds_read_b128 v[190:193], v179 offset:32768
	ds_read_b128 v[194:197], v179 offset:40960
	s_waitcnt lgkmcnt(3)
	v_mfma_f32_32x32x16_bf16 v[96:111], v[64:67], v[136:139], 0
	v_exp_f32_e32 v80, v80
	v_exp_f32_e32 v81, v81
	v_exp_f32_e32 v82, v82
	v_exp_f32_e32 v83, v83
	v_exp_f32_e32 v87, v87
	v_exp_f32_e32 v248, v93
	v_exp_f32_e32 v249, v94
	s_waitcnt lgkmcnt(2)
	v_mfma_f32_32x32x16_bf16 v[64:79], v[68:71], v[136:139], 0
	s_waitcnt lgkmcnt(1)
	v_mfma_f32_32x32x16_bf16 v[96:111], v[190:193], v[140:143], v[96:111]
	s_waitcnt lgkmcnt(0)
	v_mfma_f32_32x32x16_bf16 v[64:79], v[194:197], v[140:143], v[64:79]
	ds_read_b128 v[190:193], v180 offset:32768
	ds_read_b128 v[194:197], v180 offset:40960
	s_waitcnt lgkmcnt(1)
	v_mfma_f32_32x32x16_bf16 v[96:111], v[190:193], v[132:135], v[96:111]
	ds_read_b128 v[190:193], v181 offset:32768
	ds_read_b128 v[200:203], v181 offset:40960
	ds_read_b128 v[204:207], v182 offset:32768
	ds_read_b128 v[208:211], v182 offset:40960
	ds_read_b128 v[212:215], v183 offset:32768
	ds_read_b128 v[216:219], v183 offset:40960
	s_waitcnt lgkmcnt(6)
	v_mfma_f32_32x32x16_bf16 v[64:79], v[194:197], v[132:135], v[64:79]
	ds_read_b128 v[194:197], v184 offset:32768
	ds_read_b128 v[220:223], v184 offset:40960
	ds_read_b128 v[224:227], v185 offset:32768
	ds_read_b128 v[228:231], v185 offset:40960
	s_waitcnt lgkmcnt(9)
	v_mfma_f32_32x32x16_bf16 v[96:111], v[190:193], v[128:131], v[96:111]
	s_cmp_ge_u32 s73, s37
	s_cselect_b64 s[40:41], -1, 0
	s_and_b64 vcc, exec, s[40:41]
	s_cbranch_vccnz .LBB0_463
	s_add_i32 s74, s67, s43
	s_add_u32 s98, s38, s26
	s_addc_u32 s99, s39, s27
	s_mov_b32 m0, s74
	s_add_i32 s43, s72, s43
	global_load_lds_dwordx4 v156, s[98:99]
	s_add_u32 s100, s38, s28
	s_addc_u32 s101, s39, s29
	s_add_i32 m0, s74, 0x2000
	s_nop 0
	global_load_lds_dwordx4 v158, s[98:99]
	s_mov_b32 m0, s43
	s_nop 0
	global_load_lds_dwordx4 v162, s[100:101]
	s_add_i32 m0, s43, 0x2000
	s_nop 0
	global_load_lds_dwordx4 v160, s[100:101]
; #define SBAR() __builtin_amdgcn_sched_barrier(0)
; #define PK4(P, BASE, OUT) do { u32x4 w = {cvtpk(P[BASE + 0], P[BASE + 1]), cvtpk(P[BASE + 2], P[BASE + 3]), cvtpk(P[BASE + 4], P[BASE + 5]), cvtpk(P[BASE + 6], P[BASE + 7])}; \
;     OUT = *reinterpret_cast<bf16x8*>(&w); } while (0)
; #define PUBLISH(n) do { asm volatile("s_waitcnt vmcnt(" #n ")" ::: "memory"); asm volatile("s_waitcnt lgkmcnt(0)" ::: "memory"); __builtin_amdgcn_s_barrier(); SBAR(); } while (0)
; __device__ __forceinline__ void finishSM(f32x16& p0, f32x16& p1, float alpha, float& l_reg, bf16x8& pa0, bf16x8& pa1, bf16x8& pa2, bf16x8& pa3) {
;   for (int r = 0; r < 16; ++r) p1[r] = __builtin_amdgcn_exp2f(p1[r]);
;   float ps = 0; for (int r = 0; r < 16; ++r) ps += p0[r]; for (int r = 0; r < 16; ++r) ps += p1[r];
;   asm volatile("" : "+v"(ps));
;   l_reg = l_reg * alpha + ps;
;     ...
;   PK4(p0, 0, pa0); PK4(p0, 8, pa1); PK4(p1, 0, pa2); PK4(p1, 8, pa3);
;     ...
; }
; template <typename TQ> ...
;     ...
;     SBAR(); qkt(pA0, pA1, (const bf16*)(K_lds + ((j + 1) & 3) * (int)SHM_K), qr, r32, hi);
;     finishSM(pB0, pB1, alB, l_reg, pa0, pa1, pa2, pa3); SBAR();
;     if (j + 3 < NT) { DMA_TILE(j + 3, (j + 3) & 3); } SBAR();
;     pv_d0(o, vb0 + (j & 3) * (int)SHM_V, pa0, pa1, pa2, pa3); partialSM<true>(pA0, pA1, m_reg, mnA, alA);
;     if (j + 3 < NT) { PUBLISH(4); } else { PUBLISH(0); }
.LBB0_463:
	v_exp_f32_e32 v190, v84
	v_add_f32_e32 v84, v233, v232
	v_add_f32_e32 v84, v234, v84
	v_add_f32_e32 v84, v235, v84
	v_add_f32_e32 v84, v236, v84
	v_add_f32_e32 v84, v237, v84
	s_waitcnt lgkmcnt(8)
	v_mfma_f32_32x32x16_bf16 v[64:79], v[200:203], v[128:131], v[64:79]
	v_add_f32_e32 v84, v238, v84
	v_add_f32_e32 v84, v239, v84
	v_add_f32_e32 v84, v240, v84
	v_add_f32_e32 v84, v241, v84
	v_add_f32_e32 v84, v242, v84
	v_add_f32_e32 v84, v243, v84
	v_add_f32_e32 v84, v244, v84
	s_waitcnt lgkmcnt(7)
	v_mfma_f32_32x32x16_bf16 v[96:111], v[204:207], v[124:127], v[96:111]
	v_add_f32_e32 v84, v245, v84
	v_add_f32_e32 v84, v246, v84
	v_add_f32_e32 v84, v247, v84
	v_add_f32_e32 v84, v80, v84
	v_exp_f32_e32 v191, v85
	v_add_f32_e32 v84, v81, v84
	v_exp_f32_e32 v192, v86
	s_waitcnt lgkmcnt(6)
	v_mfma_f32_32x32x16_bf16 v[64:79], v[208:211], v[124:127], v[64:79]
	v_add_f32_e32 v84, v82, v84
	v_add_f32_e32 v84, v83, v84
	v_exp_f32_e32 v193, v88
	v_add_f32_e32 v84, v190, v84
	v_exp_f32_e32 v200, v89
	v_add_f32_e32 v84, v191, v84
	v_exp_f32_e32 v201, v90
	s_waitcnt lgkmcnt(5)
	v_mfma_f32_32x32x16_bf16 v[96:111], v[212:215], v[120:123], v[96:111]
	v_add_f32_e32 v84, v192, v84
	v_exp_f32_e32 v202, v91
	v_add_f32_e32 v84, v87, v84
	v_exp_f32_e32 v203, v92
	v_add_f32_e32 v84, v193, v84
	v_add_f32_e32 v84, v200, v84
	v_add_f32_e32 v84, v201, v84
	s_waitcnt lgkmcnt(4)
	v_mfma_f32_32x32x16_bf16 v[64:79], v[216:219], v[120:123], v[64:79]
	v_exp_f32_e32 v204, v95
	v_add_f32_e32 v84, v202, v84
	v_add_f32_e32 v84, v203, v84
	v_add_f32_e32 v84, v248, v84
	v_add_f32_e32 v84, v249, v84
	v_add_f32_e32 v199, v204, v84
	s_waitcnt lgkmcnt(3)
	v_mfma_f32_32x32x16_bf16 v[96:111], v[194:197], v[116:119], v[96:111]
	v_cvt_pk_bf16_f32 v92, v232, v233
	v_cvt_pk_bf16_f32 v93, v234, v235
	v_cvt_pk_bf16_f32 v94, v236, v237
	v_cvt_pk_bf16_f32 v95, v238, v239
	v_cvt_pk_bf16_f32 v88, v240, v241
	v_cvt_pk_bf16_f32 v89, v242, v243
	v_cvt_pk_bf16_f32 v90, v244, v245
	s_waitcnt lgkmcnt(2)
	v_mfma_f32_32x32x16_bf16 v[64:79], v[220:223], v[116:119], v[64:79]
	v_cvt_pk_bf16_f32 v91, v246, v247
	v_cvt_pk_bf16_f32 v84, v80, v81
	v_cvt_pk_bf16_f32 v85, v82, v83
	v_cvt_pk_bf16_f32 v86, v190, v191
	v_cvt_pk_bf16_f32 v87, v192, v87
	v_cvt_pk_bf16_f32 v80, v193, v200
	v_cvt_pk_bf16_f32 v81, v201, v202
	ds_read_b64_tr_b16 v[164:165], v176 offset:16384
	ds_read_b64_tr_b16 v[166:167], v176 offset:18432
	ds_read_b64_tr_b16 v[168:169], v176 offset:20480
	ds_read_b64_tr_b16 v[170:171], v176 offset:22528
	s_waitcnt lgkmcnt(5)
	v_mfma_f32_32x32x16_bf16 v[96:111], v[224:227], v[112:115], v[96:111]
	v_cvt_pk_bf16_f32 v82, v203, v248
	v_cvt_pk_bf16_f32 v83, v249, v204
	ds_read_b64_tr_b16 v[190:191], v176 offset:24576
	ds_read_b64_tr_b16 v[192:193], v176 offset:26624
	ds_read_b64_tr_b16 v[194:195], v176 offset:28672
	ds_read_b64_tr_b16 v[196:197], v176 offset:30720
	s_waitcnt lgkmcnt(8)
	v_mfma_f32_32x32x16_bf16 v[64:79], v[228:231], v[112:115], v[64:79]
	s_nop 0
	s_waitcnt lgkmcnt(6)
	v_mfma_f32_32x32x16_bf16 v[48:63], v[92:95], v[164:167], v[48:63]
	ds_read_b64_tr_b16 v[164:165], v176 offset:16896
	ds_read_b64_tr_b16 v[166:167], v176 offset:18944
	s_waitcnt lgkmcnt(6)
	v_mfma_f32_32x32x16_bf16 v[48:63], v[88:91], v[168:171], v[48:63]
	ds_read_b64_tr_b16 v[168:169], v176 offset:20992
	ds_read_b64_tr_b16 v[170:171], v176 offset:23040
	s_waitcnt lgkmcnt(6)
	v_mfma_f32_32x32x16_bf16 v[48:63], v[84:87], v[190:193], v[48:63]
	ds_read_b64_tr_b16 v[190:191], v176 offset:25088
	ds_read_b64_tr_b16 v[192:193], v176 offset:27136
	ds_read_b64_tr_b16 v[200:201], v176 offset:29184
	ds_read_b64_tr_b16 v[202:203], v176 offset:31232
	s_waitcnt lgkmcnt(8)
	v_mfma_f32_32x32x16_bf16 v[48:63], v[80:83], v[194:197], v[48:63]
	s_waitcnt lgkmcnt(6)
	v_mfma_f32_32x32x16_bf16 v[32:47], v[92:95], v[164:167], v[32:47]
	ds_read_b64_tr_b16 v[164:165], v176 offset:17408
	ds_read_b64_tr_b16 v[166:167], v176 offset:19456
	s_waitcnt lgkmcnt(6)
	v_mfma_f32_32x32x16_bf16 v[32:47], v[88:91], v[168:171], v[32:47]
	ds_read_b64_tr_b16 v[168:169], v176 offset:21504
	ds_read_b64_tr_b16 v[170:171], v176 offset:23552
	s_waitcnt lgkmcnt(6)
	v_mfma_f32_32x32x16_bf16 v[32:47], v[84:87], v[190:193], v[32:47]
	ds_read_b64_tr_b16 v[190:191], v176 offset:25600
	ds_read_b64_tr_b16 v[192:193], v176 offset:27648
	ds_read_b64_tr_b16 v[194:195], v176 offset:29696
	ds_read_b64_tr_b16 v[196:197], v176 offset:31744
	s_waitcnt lgkmcnt(8)
	v_mfma_f32_32x32x16_bf16 v[32:47], v[80:83], v[200:203], v[32:47]
	s_waitcnt lgkmcnt(6)
	v_mfma_f32_32x32x16_bf16 v[16:31], v[92:95], v[164:167], v[16:31]
	ds_read_b64_tr_b16 v[164:165], v176 offset:17920
	ds_read_b64_tr_b16 v[166:167], v176 offset:19968
	s_waitcnt lgkmcnt(6)
	v_mfma_f32_32x32x16_bf16 v[16:31], v[88:91], v[168:171], v[16:31]
	ds_read_b64_tr_b16 v[168:169], v176 offset:22016
	ds_read_b64_tr_b16 v[170:171], v176 offset:24064
	s_waitcnt lgkmcnt(6)
	v_mfma_f32_32x32x16_bf16 v[16:31], v[84:87], v[190:193], v[16:31]
	ds_read_b64_tr_b16 v[190:191], v176 offset:26112
	ds_read_b64_tr_b16 v[192:193], v176 offset:28160
	ds_read_b64_tr_b16 v[200:201], v176 offset:30208
	ds_read_b64_tr_b16 v[202:203], v176 offset:32256
	s_waitcnt lgkmcnt(8)
	v_mfma_f32_32x32x16_bf16 v[16:31], v[80:83], v[194:197], v[16:31]
	s_waitcnt lgkmcnt(6)
	v_mfma_f32_32x32x16_bf16 v[0:15], v[92:95], v[164:167], v[0:15]
	s_mov_b64 s[42:43], -1
	s_and_b64 vcc, exec, s[40:41]
	s_waitcnt lgkmcnt(4)
	v_mfma_f32_32x32x16_bf16 v[0:15], v[88:91], v[168:171], v[0:15]
	s_waitcnt lgkmcnt(2)
	v_mfma_f32_32x32x16_bf16 v[0:15], v[84:87], v[190:193], v[0:15]
	s_waitcnt lgkmcnt(0)
	v_mfma_f32_32x32x16_bf16 v[0:15], v[80:83], v[200:203], v[0:15]
	s_cbranch_vccz .LBB0_465
	s_waitcnt vmcnt(0)
	s_barrier
	s_mov_b64 s[42:43], 0

; #define SBAR() __builtin_amdgcn_sched_barrier(0)
; #define PK4(P, BASE, OUT) do { u32x4 w = {cvtpk(P[BASE + 0], P[BASE + 1]), cvtpk(P[BASE + 2], P[BASE + 3]), cvtpk(P[BASE + 4], P[BASE + 5]), cvtpk(P[BASE + 6], P[BASE + 7])}; \
;     OUT = *reinterpret_cast<bf16x8*>(&w); } while (0)
; __device__ __forceinline__ void finishSM(f32x16& p0, f32x16& p1, float alpha, float& l_reg, bf16x8& pa0, bf16x8& pa1, bf16x8& pa2, bf16x8& pa3) {
;   for (int r = 0; r < 16; ++r) p1[r] = __builtin_amdgcn_exp2f(p1[r]);
;   float ps = 0; for (int r = 0; r < 16; ++r) ps += p0[r]; for (int r = 0; r < 16; ++r) ps += p1[r];
;   asm volatile("" : "+v"(ps));
;   l_reg = l_reg * alpha + ps;
;     ...
;   PK4(p0, 0, pa0); PK4(p0, 8, pa1); PK4(p1, 0, pa2); PK4(p1, 8, pa3);
;     ...
; }
; template <typename TQ> ...
;     ...
;     SBAR(); qkt(pB0, pB1, (const bf16*)(K_lds + (j & 3) * (int)SHM_K), qr, r32, hi);
;     finishSM(pA0, pA1, alA, l_reg, pa0, pa1, pa2, pa3); SBAR();
;     DMA_TILE(j + 2, (j + 2) & 3); SBAR();
;     pv_d0(o, vb0 + ((j - 1) & 3) * (int)SHM_V, pa0, pa1, pa2, pa3); partialSM<true>(pB0, pB1, m_reg, mnB, alB);
.Lat461_b:
.Lat461_b_in:
	s_mov_b32 s40, s33
	s_addk_i32 s33, 0xc000
	s_and_b32 s42, s33, 0xc000
	s_add_i32 s33, s57, s42
	ds_read_b128 v[80:83], v178 offset:49152
	ds_read_b128 v[84:87], v178 offset:57344
	ds_read_b128 v[198:201], v179 offset:49152
	ds_read_b128 v[202:205], v179 offset:57344
	s_waitcnt lgkmcnt(3)
	v_mfma_f32_32x32x16_bf16 v[96:111], v[80:83], v[136:139], 0
	v_exp_f32_e32 v238, v64
	v_add_f32_e32 v64, v197, v196
	v_add_f32_e32 v64, v193, v64
	v_add_f32_e32 v64, v195, v64
	s_waitcnt lgkmcnt(2)
	v_mfma_f32_32x32x16_bf16 v[80:95], v[84:87], v[136:139], 0
	v_add_f32_e32 v64, v191, v64
	v_add_f32_e32 v64, v194, v64
	v_add_f32_e32 v64, v190, v64
	v_add_f32_e32 v64, v192, v64
	v_add_f32_e32 v64, v169, v64
	v_add_f32_e32 v64, v171, v64
	s_waitcnt lgkmcnt(1)
	v_mfma_f32_32x32x16_bf16 v[96:111], v[198:201], v[140:143], v[96:111]
	v_add_f32_e32 v64, v167, v64
	v_add_f32_e32 v64, v170, v64
	v_add_f32_e32 v64, v165, v64
	v_add_f32_e32 v64, v168, v64
	v_add_f32_e32 v64, v164, v64
	v_add_f32_e32 v64, v166, v64
	v_exp_f32_e32 v239, v68
	s_waitcnt lgkmcnt(0)
	v_mfma_f32_32x32x16_bf16 v[80:95], v[202:205], v[140:143], v[80:95]
	ds_read_b128 v[198:201], v180 offset:49152
	ds_read_b128 v[202:205], v180 offset:57344
	v_add_f32_e32 v64, v238, v64
	v_exp_f32_e32 v240, v69
	v_exp_f32_e32 v241, v70
	v_exp_f32_e32 v242, v71
	s_waitcnt lgkmcnt(1)
	v_mfma_f32_32x32x16_bf16 v[96:111], v[198:201], v[132:135], v[96:111]
	ds_read_b128 v[198:201], v181 offset:49152
	ds_read_b128 v[206:209], v181 offset:57344
	ds_read_b128 v[210:213], v182 offset:49152
	ds_read_b128 v[214:217], v182 offset:57344
	ds_read_b128 v[218:221], v183 offset:49152
	ds_read_b128 v[222:225], v183 offset:57344
	v_exp_f32_e32 v243, v76
	v_exp_f32_e32 v244, v77
	v_exp_f32_e32 v245, v78
	v_exp_f32_e32 v79, v79
	s_waitcnt lgkmcnt(6)
	v_mfma_f32_32x32x16_bf16 v[80:95], v[202:205], v[132:135], v[80:95]
	ds_read_b128 v[202:205], v184 offset:49152
	ds_read_b128 v[226:229], v184 offset:57344
	ds_read_b128 v[230:233], v185 offset:49152
	ds_read_b128 v[234:237], v185 offset:57344
	s_waitcnt lgkmcnt(9)
	v_mfma_f32_32x32x16_bf16 v[96:111], v[198:201], v[128:131], v[96:111]
	v_exp_f32_e32 v199, v65
	v_exp_f32_e32 v200, v66
	v_exp_f32_e32 v201, v67
	v_add_f32_e32 v64, v199, v64
	v_add_f32_e32 v64, v200, v64
	v_add_f32_e32 v64, v201, v64
	s_waitcnt lgkmcnt(8)
	v_mfma_f32_32x32x16_bf16 v[80:95], v[206:209], v[128:131], v[80:95]
	v_exp_f32_e32 v206, v72
	v_add_f32_e32 v64, v239, v64
	v_exp_f32_e32 v207, v73
	v_add_f32_e32 v64, v240, v64
	v_exp_f32_e32 v208, v74
	v_add_f32_e32 v64, v241, v64
	v_exp_f32_e32 v209, v75
	s_waitcnt lgkmcnt(7)
	v_mfma_f32_32x32x16_bf16 v[96:111], v[210:213], v[124:127], v[96:111]
	v_add_f32_e32 v64, v242, v64
	v_add_f32_e32 v64, v206, v64
	v_add_f32_e32 v64, v207, v64
	v_add_f32_e32 v64, v208, v64
	v_add_f32_e32 v64, v209, v64
	v_add_f32_e32 v64, v243, v64
	v_add_f32_e32 v64, v244, v64
	s_waitcnt lgkmcnt(6)
	v_mfma_f32_32x32x16_bf16 v[80:95], v[214:217], v[124:127], v[80:95]
	v_add_f32_e32 v64, v245, v64
	v_add_f32_e32 v198, v79, v64
	v_cvt_pk_bf16_f32 v64, v196, v197
	v_cvt_pk_bf16_f32 v65, v193, v195
	v_cvt_pk_bf16_f32 v66, v191, v194
	v_cvt_pk_bf16_f32 v67, v190, v192
	s_waitcnt lgkmcnt(5)
	v_mfma_f32_32x32x16_bf16 v[96:111], v[218:221], v[120:123], v[96:111]
	v_cvt_pk_bf16_f32 v68, v169, v171
	v_cvt_pk_bf16_f32 v69, v167, v170
	v_cvt_pk_bf16_f32 v70, v165, v168
	v_cvt_pk_bf16_f32 v71, v164, v166
	v_cvt_pk_bf16_f32 v72, v238, v199
	v_cvt_pk_bf16_f32 v73, v200, v201
	v_cvt_pk_bf16_f32 v74, v239, v240
	s_waitcnt lgkmcnt(4)
	v_mfma_f32_32x32x16_bf16 v[80:95], v[222:225], v[120:123], v[80:95]
	v_cvt_pk_bf16_f32 v75, v241, v242
	v_cvt_pk_bf16_f32 v76, v206, v207
	v_cvt_pk_bf16_f32 v77, v208, v209
	v_cvt_pk_bf16_f32 v78, v243, v244
	v_cvt_pk_bf16_f32 v79, v245, v79
	s_waitcnt lgkmcnt(3)
	v_mfma_f32_32x32x16_bf16 v[96:111], v[202:205], v[116:119], v[96:111]
	s_add_i32 s33, s40, 0x8000
	s_and_b32 s43, s33, 0xc000
	ds_read_b64_tr_b16 v[190:191], v176 offset:32768
	ds_read_b64_tr_b16 v[192:193], v176 offset:34816
	ds_read_b64_tr_b16 v[194:195], v176 offset:36864
	ds_read_b64_tr_b16 v[196:197], v176 offset:38912
	s_waitcnt lgkmcnt(6)
	v_mfma_f32_32x32x16_bf16 v[80:95], v[226:229], v[116:119], v[80:95]
	ds_read_b64_tr_b16 v[200:201], v176 offset:40960
	ds_read_b64_tr_b16 v[202:203], v176 offset:43008
	ds_read_b64_tr_b16 v[204:205], v176 offset:45056
	ds_read_b64_tr_b16 v[206:207], v176 offset:47104
	s_add_i32 s74, s40, 0x4000
	s_and_b32 s74, s74, 0xc000
	s_add_u32 s98, s38, s22
	s_addc_u32 s99, s39, s23
	s_add_i32 s41, s67, s74
	s_add_u32 s100, s38, s24
	s_addc_u32 s101, s39, s25
	s_mov_b32 m0, s41
	s_add_i32 s74, s72, s74
	global_load_lds_dwordx4 v156, s[98:99]
	s_waitcnt lgkmcnt(9)
	v_mfma_f32_32x32x16_bf16 v[96:111], v[230:233], v[112:115], v[96:111]
	s_add_i32 m0, s41, 0x2000
	s_nop 0
	global_load_lds_dwordx4 v158, s[98:99]
	s_mov_b32 m0, s74
	s_nop 0
	global_load_lds_dwordx4 v162, s[100:101]
	s_waitcnt lgkmcnt(8)
; #define SBAR() __builtin_amdgcn_sched_barrier(0)
; #define PUBLISH(n) do { asm volatile("s_waitcnt vmcnt(" #n ")" ::: "memory"); asm volatile("s_waitcnt lgkmcnt(0)" ::: "memory"); __builtin_amdgcn_s_barrier(); SBAR(); } while (0)
; template <typename TQ> ...
;     ...
;     pv_d0(o, vb0 + ((j - 1) & 3) * (int)SHM_V, pa0, pa1, pa2, pa3); partialSM<true>(pB0, pB1, m_reg, mnB, alB);
;     PUBLISH(4);
;     SBAR(); qkt(pA0, pA1, (const bf16*)(K_lds + ((j + 1) & 3) * (int)SHM_K), qr, r32, hi);
;     finishSM(pB0, pB1, alB, l_reg, pa0, pa1, pa2, pa3); SBAR();
;     if (j + 3 < NT) { DMA_TILE(j + 3, (j + 3) & 3); } SBAR();
	v_mfma_f32_32x32x16_bf16 v[80:95], v[234:237], v[112:115], v[80:95]
	s_add_i32 m0, s74, 0x2000
	s_nop 0
	global_load_lds_dwordx4 v160, s[100:101]
	s_nop 0
	s_waitcnt lgkmcnt(6)
	v_mfma_f32_32x32x16_bf16 v[48:63], v[64:67], v[190:193], v[48:63]
	v_exp_f32_e32 v232, v96
	ds_read_b64_tr_b16 v[190:191], v176 offset:33280
	ds_read_b64_tr_b16 v[192:193], v176 offset:35328
	s_waitcnt lgkmcnt(6)
	v_mfma_f32_32x32x16_bf16 v[48:63], v[68:71], v[194:197], v[48:63]
	v_exp_f32_e32 v233, v97
	ds_read_b64_tr_b16 v[194:195], v176 offset:37376
	ds_read_b64_tr_b16 v[196:197], v176 offset:39424
	s_waitcnt lgkmcnt(6)
	v_mfma_f32_32x32x16_bf16 v[48:63], v[72:75], v[200:203], v[48:63]
	v_exp_f32_e32 v234, v98
	ds_read_b64_tr_b16 v[200:201], v176 offset:41472
	ds_read_b64_tr_b16 v[202:203], v176 offset:43520
	ds_read_b64_tr_b16 v[208:209], v176 offset:45568
	ds_read_b64_tr_b16 v[210:211], v176 offset:47616
	s_waitcnt lgkmcnt(8)
	v_mfma_f32_32x32x16_bf16 v[48:63], v[76:79], v[204:207], v[48:63]
	v_exp_f32_e32 v235, v99
	s_waitcnt lgkmcnt(6)
	v_mfma_f32_32x32x16_bf16 v[32:47], v[64:67], v[190:193], v[32:47]
	v_exp_f32_e32 v236, v100
	ds_read_b64_tr_b16 v[190:191], v176 offset:33792
	ds_read_b64_tr_b16 v[192:193], v176 offset:35840
	s_waitcnt lgkmcnt(6)
	v_mfma_f32_32x32x16_bf16 v[32:47], v[68:71], v[194:197], v[32:47]
	v_exp_f32_e32 v237, v101
	ds_read_b64_tr_b16 v[194:195], v176 offset:37888
	ds_read_b64_tr_b16 v[196:197], v176 offset:39936
	s_waitcnt lgkmcnt(6)
	v_mfma_f32_32x32x16_bf16 v[32:47], v[72:75], v[200:203], v[32:47]
	v_exp_f32_e32 v238, v102
	ds_read_b64_tr_b16 v[200:201], v176 offset:41984
	ds_read_b64_tr_b16 v[202:203], v176 offset:44032
	ds_read_b64_tr_b16 v[204:205], v176 offset:46080
	ds_read_b64_tr_b16 v[206:207], v176 offset:48128
	s_waitcnt lgkmcnt(8)
	v_mfma_f32_32x32x16_bf16 v[32:47], v[76:79], v[208:211], v[32:47]
	v_exp_f32_e32 v239, v103
	v_exp_f32_e32 v240, v104
	s_waitcnt lgkmcnt(6)
	v_mfma_f32_32x32x16_bf16 v[16:31], v[64:67], v[190:193], v[16:31]
	v_exp_f32_e32 v241, v105
	ds_read_b64_tr_b16 v[190:191], v176 offset:34304
	ds_read_b64_tr_b16 v[192:193], v176 offset:36352
	s_waitcnt lgkmcnt(6)
	v_mfma_f32_32x32x16_bf16 v[16:31], v[68:71], v[194:197], v[16:31]
	v_exp_f32_e32 v242, v106
	ds_read_b64_tr_b16 v[194:195], v176 offset:38400
	ds_read_b64_tr_b16 v[196:197], v176 offset:40448
	s_waitcnt lgkmcnt(6)
	v_mfma_f32_32x32x16_bf16 v[16:31], v[72:75], v[200:203], v[16:31]
	v_exp_f32_e32 v243, v107
	ds_read_b64_tr_b16 v[200:201], v176 offset:42496
	ds_read_b64_tr_b16 v[202:203], v176 offset:44544
	ds_read_b64_tr_b16 v[208:209], v176 offset:46592
	ds_read_b64_tr_b16 v[210:211], v176 offset:48640
	s_waitcnt lgkmcnt(8)
	v_mfma_f32_32x32x16_bf16 v[16:31], v[76:79], v[204:207], v[16:31]
	v_exp_f32_e32 v244, v108
	s_waitcnt lgkmcnt(6)
	v_mfma_f32_32x32x16_bf16 v[0:15], v[64:67], v[190:193], v[0:15]
	v_exp_f32_e32 v245, v109
	s_waitcnt lgkmcnt(4)
	v_mfma_f32_32x32x16_bf16 v[0:15], v[68:71], v[194:197], v[0:15]
	v_exp_f32_e32 v246, v110
	s_waitcnt lgkmcnt(2)
	v_mfma_f32_32x32x16_bf16 v[0:15], v[72:75], v[200:203], v[0:15]
	v_exp_f32_e32 v247, v111
	s_waitcnt vmcnt(4)
	s_waitcnt lgkmcnt(0)
	s_barrier
	v_mfma_f32_32x32x16_bf16 v[0:15], v[76:79], v[208:211], v[0:15]
	s_and_b32 s40, s40, 0xc000
	s_add_i32 s40, s57, s40
	ds_read_b128 v[64:67], v178
	ds_read_b128 v[68:71], v178 offset:8192
	ds_read_b128 v[190:193], v179
	ds_read_b128 v[194:197], v179 offset:8192
	s_waitcnt lgkmcnt(3)
	v_mfma_f32_32x32x16_bf16 v[96:111], v[64:67], v[136:139], 0
	v_exp_f32_e32 v80, v80
	v_exp_f32_e32 v81, v81
	v_exp_f32_e32 v82, v82
	v_exp_f32_e32 v83, v83
	v_exp_f32_e32 v87, v87
	v_exp_f32_e32 v248, v93
	v_exp_f32_e32 v249, v94
	s_waitcnt lgkmcnt(2)
	v_mfma_f32_32x32x16_bf16 v[64:79], v[68:71], v[136:139], 0
	s_waitcnt lgkmcnt(1)
	v_mfma_f32_32x32x16_bf16 v[96:111], v[190:193], v[140:143], v[96:111]
	s_waitcnt lgkmcnt(0)
	v_mfma_f32_32x32x16_bf16 v[64:79], v[194:197], v[140:143], v[64:79]
	ds_read_b128 v[190:193], v180
	ds_read_b128 v[194:197], v180 offset:8192
	s_waitcnt lgkmcnt(1)
	v_mfma_f32_32x32x16_bf16 v[96:111], v[190:193], v[132:135], v[96:111]
	ds_read_b128 v[190:193], v181
	ds_read_b128 v[200:203], v181 offset:8192
	ds_read_b128 v[204:207], v182
	ds_read_b128 v[208:211], v182 offset:8192
	ds_read_b128 v[212:215], v183
	ds_read_b128 v[216:219], v183 offset:8192
	s_waitcnt lgkmcnt(6)
	v_mfma_f32_32x32x16_bf16 v[64:79], v[194:197], v[132:135], v[64:79]
	ds_read_b128 v[194:197], v184
	ds_read_b128 v[220:223], v184 offset:8192
	ds_read_b128 v[224:227], v185
	ds_read_b128 v[228:231], v185 offset:8192
	s_waitcnt lgkmcnt(9)
	v_mfma_f32_32x32x16_bf16 v[96:111], v[190:193], v[128:131], v[96:111]
	s_cmp_ge_u32 s73, s37
	s_cselect_b64 s[40:41], -1, 0
	s_and_b64 vcc, exec, s[40:41]
	s_cbranch_vccnz .Lat463_b

; #define SBAR() __builtin_amdgcn_sched_barrier(0)
; #define PK4(P, BASE, OUT) do { u32x4 w = {cvtpk(P[BASE + 0], P[BASE + 1]), cvtpk(P[BASE + 2], P[BASE + 3]), cvtpk(P[BASE + 4], P[BASE + 5]), cvtpk(P[BASE + 6], P[BASE + 7])}; \
;     OUT = *reinterpret_cast<bf16x8*>(&w); } while (0)
; #define PUBLISH(n) do { asm volatile("s_waitcnt vmcnt(" #n ")" ::: "memory"); asm volatile("s_waitcnt lgkmcnt(0)" ::: "memory"); __builtin_amdgcn_s_barrier(); SBAR(); } while (0)
; __device__ __forceinline__ void finishSM(f32x16& p0, f32x16& p1, float alpha, float& l_reg, bf16x8& pa0, bf16x8& pa1, bf16x8& pa2, bf16x8& pa3) {
;   for (int r = 0; r < 16; ++r) p1[r] = __builtin_amdgcn_exp2f(p1[r]);
;   float ps = 0; for (int r = 0; r < 16; ++r) ps += p0[r]; for (int r = 0; r < 16; ++r) ps += p1[r];
;   asm volatile("" : "+v"(ps));
;   l_reg = l_reg * alpha + ps;
;     ...
;   PK4(p0, 0, pa0); PK4(p0, 8, pa1); PK4(p1, 0, pa2); PK4(p1, 8, pa3);
;     ...
; }
; template <typename TQ> ...
;     ...
;     SBAR(); qkt(pA0, pA1, (const bf16*)(K_lds + ((j + 1) & 3) * (int)SHM_K), qr, r32, hi);
;     finishSM(pB0, pB1, alB, l_reg, pa0, pa1, pa2, pa3); SBAR();
;     if (j + 3 < NT) { DMA_TILE(j + 3, (j + 3) & 3); } SBAR();
;     pv_d0(o, vb0 + (j & 3) * (int)SHM_V, pa0, pa1, pa2, pa3); partialSM<true>(pA0, pA1, m_reg, mnA, alA);
;     if (j + 3 < NT) { PUBLISH(4); } else { PUBLISH(0); }
	s_add_i32 s74, s67, s43
	s_add_u32 s98, s38, s26
	s_addc_u32 s99, s39, s27
	s_mov_b32 m0, s74
	s_add_i32 s43, s72, s43
	global_load_lds_dwordx4 v156, s[98:99]
	s_add_u32 s100, s38, s28
	s_addc_u32 s101, s39, s29
	s_add_i32 m0, s74, 0x2000
	s_nop 0
	global_load_lds_dwordx4 v158, s[98:99]
	s_mov_b32 m0, s43
	s_nop 0
	global_load_lds_dwordx4 v162, s[100:101]
	s_add_i32 m0, s43, 0x2000
	s_nop 0
	global_load_lds_dwordx4 v160, s[100:101]
.Lat463_b:
	v_exp_f32_e32 v190, v84
	v_add_f32_e32 v84, v233, v232
	v_add_f32_e32 v84, v234, v84
	v_add_f32_e32 v84, v235, v84
	v_add_f32_e32 v84, v236, v84
	v_add_f32_e32 v84, v237, v84
	s_waitcnt lgkmcnt(8)
	v_mfma_f32_32x32x16_bf16 v[64:79], v[200:203], v[128:131], v[64:79]
	v_add_f32_e32 v84, v238, v84
	v_add_f32_e32 v84, v239, v84
	v_add_f32_e32 v84, v240, v84
	v_add_f32_e32 v84, v241, v84
	v_add_f32_e32 v84, v242, v84
	v_add_f32_e32 v84, v243, v84
	v_add_f32_e32 v84, v244, v84
	s_waitcnt lgkmcnt(7)
	v_mfma_f32_32x32x16_bf16 v[96:111], v[204:207], v[124:127], v[96:111]
	v_add_f32_e32 v84, v245, v84
	v_add_f32_e32 v84, v246, v84
	v_add_f32_e32 v84, v247, v84
	v_add_f32_e32 v84, v80, v84
	v_exp_f32_e32 v191, v85
	v_add_f32_e32 v84, v81, v84
	v_exp_f32_e32 v192, v86
	s_waitcnt lgkmcnt(6)
	v_mfma_f32_32x32x16_bf16 v[64:79], v[208:211], v[124:127], v[64:79]
	v_add_f32_e32 v84, v82, v84
	v_add_f32_e32 v84, v83, v84
	v_exp_f32_e32 v193, v88
	v_add_f32_e32 v84, v190, v84
	v_exp_f32_e32 v200, v89
	v_add_f32_e32 v84, v191, v84
	v_exp_f32_e32 v201, v90
	s_waitcnt lgkmcnt(5)
	v_mfma_f32_32x32x16_bf16 v[96:111], v[212:215], v[120:123], v[96:111]
	v_add_f32_e32 v84, v192, v84
	v_exp_f32_e32 v202, v91
	v_add_f32_e32 v84, v87, v84
	v_exp_f32_e32 v203, v92
	v_add_f32_e32 v84, v193, v84
	v_add_f32_e32 v84, v200, v84
	v_add_f32_e32 v84, v201, v84
	s_waitcnt lgkmcnt(4)
	v_mfma_f32_32x32x16_bf16 v[64:79], v[216:219], v[120:123], v[64:79]
	v_exp_f32_e32 v204, v95
	v_add_f32_e32 v84, v202, v84
	v_add_f32_e32 v84, v203, v84
	v_add_f32_e32 v84, v248, v84
	v_add_f32_e32 v84, v249, v84
	v_add_f32_e32 v199, v204, v84
	s_waitcnt lgkmcnt(3)
	v_mfma_f32_32x32x16_bf16 v[96:111], v[194:197], v[116:119], v[96:111]
	v_cvt_pk_bf16_f32 v92, v232, v233
	v_cvt_pk_bf16_f32 v93, v234, v235
	v_cvt_pk_bf16_f32 v94, v236, v237
	v_cvt_pk_bf16_f32 v95, v238, v239
	v_cvt_pk_bf16_f32 v88, v240, v241
	v_cvt_pk_bf16_f32 v89, v242, v243
	v_cvt_pk_bf16_f32 v90, v244, v245
	s_waitcnt lgkmcnt(2)
	v_mfma_f32_32x32x16_bf16 v[64:79], v[220:223], v[116:119], v[64:79]
	v_cvt_pk_bf16_f32 v91, v246, v247
	v_cvt_pk_bf16_f32 v84, v80, v81
	v_cvt_pk_bf16_f32 v85, v82, v83
	v_cvt_pk_bf16_f32 v86, v190, v191
	v_cvt_pk_bf16_f32 v87, v192, v87
	v_cvt_pk_bf16_f32 v80, v193, v200
	v_cvt_pk_bf16_f32 v81, v201, v202
	ds_read_b64_tr_b16 v[164:165], v176 offset:49152
	ds_read_b64_tr_b16 v[166:167], v176 offset:51200
	ds_read_b64_tr_b16 v[168:169], v176 offset:53248
	ds_read_b64_tr_b16 v[170:171], v176 offset:55296
	s_waitcnt lgkmcnt(5)
	v_mfma_f32_32x32x16_bf16 v[96:111], v[224:227], v[112:115], v[96:111]
	v_cvt_pk_bf16_f32 v82, v203, v248
	v_cvt_pk_bf16_f32 v83, v249, v204
	ds_read_b64_tr_b16 v[190:191], v176 offset:57344
	ds_read_b64_tr_b16 v[192:193], v176 offset:59392
	ds_read_b64_tr_b16 v[194:195], v176 offset:61440
	ds_read_b64_tr_b16 v[196:197], v176 offset:63488
	s_waitcnt lgkmcnt(8)
	v_mfma_f32_32x32x16_bf16 v[64:79], v[228:231], v[112:115], v[64:79]
	s_nop 0
	s_waitcnt lgkmcnt(6)
	v_mfma_f32_32x32x16_bf16 v[48:63], v[92:95], v[164:167], v[48:63]
	ds_read_b64_tr_b16 v[164:165], v176 offset:49664
	ds_read_b64_tr_b16 v[166:167], v176 offset:51712
	s_waitcnt lgkmcnt(6)
	v_mfma_f32_32x32x16_bf16 v[48:63], v[88:91], v[168:171], v[48:63]
	ds_read_b64_tr_b16 v[168:169], v176 offset:53760
	ds_read_b64_tr_b16 v[170:171], v176 offset:55808
	s_waitcnt lgkmcnt(6)
	v_mfma_f32_32x32x16_bf16 v[48:63], v[84:87], v[190:193], v[48:63]
	ds_read_b64_tr_b16 v[190:191], v176 offset:57856
	ds_read_b64_tr_b16 v[192:193], v176 offset:59904
	ds_read_b64_tr_b16 v[200:201], v176 offset:61952
	ds_read_b64_tr_b16 v[202:203], v176 offset:64000
	s_waitcnt lgkmcnt(8)
	v_mfma_f32_32x32x16_bf16 v[48:63], v[80:83], v[194:197], v[48:63]
	s_waitcnt lgkmcnt(6)
	v_mfma_f32_32x32x16_bf16 v[32:47], v[92:95], v[164:167], v[32:47]
	ds_read_b64_tr_b16 v[164:165], v176 offset:50176
	ds_read_b64_tr_b16 v[166:167], v176 offset:52224
	s_waitcnt lgkmcnt(6)
	v_mfma_f32_32x32x16_bf16 v[32:47], v[88:91], v[168:171], v[32:47]
	ds_read_b64_tr_b16 v[168:169], v176 offset:54272
	ds_read_b64_tr_b16 v[170:171], v176 offset:56320
	s_waitcnt lgkmcnt(6)
	v_mfma_f32_32x32x16_bf16 v[32:47], v[84:87], v[190:193], v[32:47]
	ds_read_b64_tr_b16 v[190:191], v176 offset:58368
	ds_read_b64_tr_b16 v[192:193], v176 offset:60416
	ds_read_b64_tr_b16 v[194:195], v176 offset:62464
	ds_read_b64_tr_b16 v[196:197], v176 offset:64512
	s_waitcnt lgkmcnt(8)
	v_mfma_f32_32x32x16_bf16 v[32:47], v[80:83], v[200:203], v[32:47]
	s_waitcnt lgkmcnt(6)
	v_mfma_f32_32x32x16_bf16 v[16:31], v[92:95], v[164:167], v[16:31]
	ds_read_b64_tr_b16 v[164:165], v176 offset:50688
	ds_read_b64_tr_b16 v[166:167], v176 offset:52736
	s_waitcnt lgkmcnt(6)
	v_mfma_f32_32x32x16_bf16 v[16:31], v[88:91], v[168:171], v[16:31]
	ds_read_b64_tr_b16 v[168:169], v176 offset:54784
	ds_read_b64_tr_b16 v[170:171], v176 offset:56832
	s_waitcnt lgkmcnt(6)
	v_mfma_f32_32x32x16_bf16 v[16:31], v[84:87], v[190:193], v[16:31]
	ds_read_b64_tr_b16 v[190:191], v176 offset:58880
	ds_read_b64_tr_b16 v[192:193], v176 offset:60928
	ds_read_b64_tr_b16 v[200:201], v176 offset:62976
	ds_read_b64_tr_b16 v[202:203], v176 offset:65024
	s_waitcnt lgkmcnt(8)
	v_mfma_f32_32x32x16_bf16 v[16:31], v[80:83], v[194:197], v[16:31]
	s_waitcnt lgkmcnt(6)
	v_mfma_f32_32x32x16_bf16 v[0:15], v[92:95], v[164:167], v[0:15]
	s_mov_b64 s[42:43], -1
	s_and_b64 vcc, exec, s[40:41]
	s_waitcnt lgkmcnt(4)
	v_mfma_f32_32x32x16_bf16 v[0:15], v[88:91], v[168:171], v[0:15]
	s_waitcnt lgkmcnt(2)
	v_mfma_f32_32x32x16_bf16 v[0:15], v[84:87], v[190:193], v[0:15]
	s_waitcnt lgkmcnt(0)
	v_mfma_f32_32x32x16_bf16 v[0:15], v[80:83], v[200:203], v[0:15]
	s_cbranch_vccz .Lat465_b

; #define PUBLISH(n) do { asm volatile("s_waitcnt vmcnt(" #n ")" ::: "memory"); asm volatile("s_waitcnt lgkmcnt(0)" ::: "memory"); __builtin_amdgcn_s_barrier(); SBAR(); } while (0)
; template <typename TQ> ...
;     ...
;     if (j + 3 < NT) { PUBLISH(4); } else { PUBLISH(0); }
	s_waitcnt vmcnt(0)
	s_barrier
	s_mov_b64 s[42:43], 0

; #define SBAR() __builtin_amdgcn_sched_barrier(0)
; #define PK4(P, BASE, OUT) do { u32x4 w = {cvtpk(P[BASE + 0], P[BASE + 1]), cvtpk(P[BASE + 2], P[BASE + 3]), cvtpk(P[BASE + 4], P[BASE + 5]), cvtpk(P[BASE + 6], P[BASE + 7])}; \
;     OUT = *reinterpret_cast<bf16x8*>(&w); } while (0)
; __device__ __forceinline__ void finishSM(f32x16& p0, f32x16& p1, float alpha, float& l_reg, bf16x8& pa0, bf16x8& pa1, bf16x8& pa2, bf16x8& pa3) {
;   for (int r = 0; r < 16; ++r) p1[r] = __builtin_amdgcn_exp2f(p1[r]);
;   float ps = 0; for (int r = 0; r < 16; ++r) ps += p0[r]; for (int r = 0; r < 16; ++r) ps += p1[r];
;   asm volatile("" : "+v"(ps));
;   l_reg = l_reg * alpha + ps;
;     ...
;   PK4(p0, 0, pa0); PK4(p0, 8, pa1); PK4(p1, 0, pa2); PK4(p1, 8, pa3);
;     ...
; }
; template <typename TQ> ...
;     ...
;   for (int j = 1; j + 1 < NT; j += 2) {
;     SBAR(); qkt(pB0, pB1, (const bf16*)(K_lds + (j & 3) * (int)SHM_K), qr, r32, hi);
;     finishSM(pA0, pA1, alA, l_reg, pa0, pa1, pa2, pa3); SBAR();
;     DMA_TILE(j + 2, (j + 2) & 3); SBAR();
;     pv_d0(o, vb0 + ((j - 1) & 3) * (int)SHM_V, pa0, pa1, pa2, pa3); partialSM<true>(pB0, pB1, m_reg, mnB, alB);
.LBB0_1365:
	s_bitcmp1_b32 s72, 1
	s_cbranch_scc1 .Lat1365_b_in
	s_mov_b32 s40, s33
	s_addk_i32 s33, 0xc000
	s_and_b32 s42, s33, 0xc000
	s_add_i32 s33, s56, s42
	ds_read_b128 v[80:83], v178 offset:16384
	ds_read_b128 v[84:87], v178 offset:24576
	ds_read_b128 v[198:201], v179 offset:16384
	ds_read_b128 v[202:205], v179 offset:24576
	s_waitcnt lgkmcnt(3)
	v_mfma_f32_32x32x16_bf16 v[96:111], v[80:83], v[136:139], 0
	v_exp_f32_e32 v238, v64
	v_add_f32_e32 v64, v197, v196
	v_add_f32_e32 v64, v193, v64
	v_add_f32_e32 v64, v195, v64
	s_waitcnt lgkmcnt(2)
	v_mfma_f32_32x32x16_bf16 v[80:95], v[84:87], v[136:139], 0
	v_add_f32_e32 v64, v191, v64
	v_add_f32_e32 v64, v194, v64
	v_add_f32_e32 v64, v190, v64
	v_add_f32_e32 v64, v192, v64
	v_add_f32_e32 v64, v169, v64
	v_add_f32_e32 v64, v171, v64
	s_waitcnt lgkmcnt(1)
	v_mfma_f32_32x32x16_bf16 v[96:111], v[198:201], v[140:143], v[96:111]
	v_add_f32_e32 v64, v167, v64
	v_add_f32_e32 v64, v170, v64
	v_add_f32_e32 v64, v165, v64
	v_add_f32_e32 v64, v168, v64
	v_add_f32_e32 v64, v164, v64
	v_add_f32_e32 v64, v166, v64
	v_exp_f32_e32 v239, v68
	s_waitcnt lgkmcnt(0)
	v_mfma_f32_32x32x16_bf16 v[80:95], v[202:205], v[140:143], v[80:95]
	ds_read_b128 v[198:201], v180 offset:16384
	ds_read_b128 v[202:205], v180 offset:24576
	v_add_f32_e32 v64, v238, v64
	v_exp_f32_e32 v240, v69
	v_exp_f32_e32 v241, v70
	v_exp_f32_e32 v242, v71
	s_waitcnt lgkmcnt(1)
	v_mfma_f32_32x32x16_bf16 v[96:111], v[198:201], v[132:135], v[96:111]
	ds_read_b128 v[198:201], v181 offset:16384
	ds_read_b128 v[206:209], v181 offset:24576
	ds_read_b128 v[210:213], v182 offset:16384
	ds_read_b128 v[214:217], v182 offset:24576
	ds_read_b128 v[218:221], v183 offset:16384
	ds_read_b128 v[222:225], v183 offset:24576
	v_exp_f32_e32 v243, v76
	v_exp_f32_e32 v244, v77
	v_exp_f32_e32 v245, v78
	v_exp_f32_e32 v79, v79
	s_waitcnt lgkmcnt(6)
	v_mfma_f32_32x32x16_bf16 v[80:95], v[202:205], v[132:135], v[80:95]
	ds_read_b128 v[202:205], v184 offset:16384
	ds_read_b128 v[226:229], v184 offset:24576
	ds_read_b128 v[230:233], v185 offset:16384
	ds_read_b128 v[234:237], v185 offset:24576
	s_waitcnt lgkmcnt(9)
	v_mfma_f32_32x32x16_bf16 v[96:111], v[198:201], v[128:131], v[96:111]
	v_exp_f32_e32 v199, v65
	v_exp_f32_e32 v200, v66
	v_exp_f32_e32 v201, v67
	v_add_f32_e32 v64, v199, v64
	v_add_f32_e32 v64, v200, v64
	v_add_f32_e32 v64, v201, v64
	s_waitcnt lgkmcnt(8)
	v_mfma_f32_32x32x16_bf16 v[80:95], v[206:209], v[128:131], v[80:95]
	v_exp_f32_e32 v206, v72
	v_add_f32_e32 v64, v239, v64
	v_exp_f32_e32 v207, v73
	v_add_f32_e32 v64, v240, v64
	v_exp_f32_e32 v208, v74
	v_add_f32_e32 v64, v241, v64
	v_exp_f32_e32 v209, v75
	s_waitcnt lgkmcnt(7)
	v_mfma_f32_32x32x16_bf16 v[96:111], v[210:213], v[124:127], v[96:111]
	v_add_f32_e32 v64, v242, v64
	v_add_f32_e32 v64, v206, v64
	v_add_f32_e32 v64, v207, v64
	v_add_f32_e32 v64, v208, v64
	v_add_f32_e32 v64, v209, v64
	v_add_f32_e32 v64, v243, v64
	v_add_f32_e32 v64, v244, v64
	s_waitcnt lgkmcnt(6)
	v_mfma_f32_32x32x16_bf16 v[80:95], v[214:217], v[124:127], v[80:95]
	v_add_f32_e32 v64, v245, v64
	v_add_f32_e32 v198, v79, v64
	v_cvt_pk_bf16_f32 v64, v196, v197
	v_cvt_pk_bf16_f32 v65, v193, v195
	v_cvt_pk_bf16_f32 v66, v191, v194
	v_cvt_pk_bf16_f32 v67, v190, v192
	s_waitcnt lgkmcnt(5)
	v_mfma_f32_32x32x16_bf16 v[96:111], v[218:221], v[120:123], v[96:111]
	v_cvt_pk_bf16_f32 v68, v169, v171
	v_cvt_pk_bf16_f32 v69, v167, v170
	v_cvt_pk_bf16_f32 v70, v165, v168
	v_cvt_pk_bf16_f32 v71, v164, v166
	v_cvt_pk_bf16_f32 v72, v238, v199
	v_cvt_pk_bf16_f32 v73, v200, v201
	v_cvt_pk_bf16_f32 v74, v239, v240
	s_waitcnt lgkmcnt(4)
	v_mfma_f32_32x32x16_bf16 v[80:95], v[222:225], v[120:123], v[80:95]
	v_cvt_pk_bf16_f32 v75, v241, v242
	v_cvt_pk_bf16_f32 v76, v206, v207
	v_cvt_pk_bf16_f32 v77, v208, v209
	v_cvt_pk_bf16_f32 v78, v243, v244
	v_cvt_pk_bf16_f32 v79, v245, v79
	s_waitcnt lgkmcnt(3)
	v_mfma_f32_32x32x16_bf16 v[96:111], v[202:205], v[116:119], v[96:111]
	s_add_i32 s33, s40, 0x8000
	s_and_b32 s43, s33, 0xc000
	ds_read_b64_tr_b16 v[190:191], v176
	ds_read_b64_tr_b16 v[192:193], v176 offset:2048
	ds_read_b64_tr_b16 v[194:195], v176 offset:4096
	ds_read_b64_tr_b16 v[196:197], v176 offset:6144
	s_waitcnt lgkmcnt(6)
	v_mfma_f32_32x32x16_bf16 v[80:95], v[226:229], v[116:119], v[80:95]
	ds_read_b64_tr_b16 v[200:201], v176 offset:8192
	ds_read_b64_tr_b16 v[202:203], v176 offset:10240
	ds_read_b64_tr_b16 v[204:205], v176 offset:12288
	ds_read_b64_tr_b16 v[206:207], v176 offset:14336
	s_add_i32 s73, s40, 0x4000
	s_and_b32 s73, s73, 0xc000
	s_add_u32 s98, s38, s22
	s_addc_u32 s99, s39, s23
	s_add_i32 s41, s66, s73
	s_add_u32 s100, s38, s24
	s_addc_u32 s101, s39, s25
	s_mov_b32 m0, s41
	s_add_i32 s73, s67, s73
	global_load_lds_dwordx4 v156, s[98:99]
	s_waitcnt lgkmcnt(9)
	v_mfma_f32_32x32x16_bf16 v[96:111], v[230:233], v[112:115], v[96:111]
	s_add_i32 m0, s41, 0x2000
	s_nop 0
	global_load_lds_dwordx4 v158, s[98:99]
	s_mov_b32 m0, s73
	s_nop 0
	global_load_lds_dwordx4 v162, s[100:101]
	s_waitcnt lgkmcnt(8)
	v_mfma_f32_32x32x16_bf16 v[80:95], v[234:237], v[112:115], v[80:95]
	s_add_i32 m0, s73, 0x2000
	s_nop 0
	global_load_lds_dwordx4 v160, s[100:101]
	s_nop 0
	s_waitcnt lgkmcnt(6)
; #define SBAR() __builtin_amdgcn_sched_barrier(0)
; #define PUBLISH(n) do { asm volatile("s_waitcnt vmcnt(" #n ")" ::: "memory"); asm volatile("s_waitcnt lgkmcnt(0)" ::: "memory"); __builtin_amdgcn_s_barrier(); SBAR(); } while (0)
; template <typename TQ> ...
;     ...
;     pv_d0(o, vb0 + ((j - 1) & 3) * (int)SHM_V, pa0, pa1, pa2, pa3); partialSM<true>(pB0, pB1, m_reg, mnB, alB);
;     PUBLISH(4);
;     SBAR(); qkt(pA0, pA1, (const bf16*)(K_lds + ((j + 1) & 3) * (int)SHM_K), qr, r32, hi);
;     finishSM(pB0, pB1, alB, l_reg, pa0, pa1, pa2, pa3); SBAR();
;     if (j + 3 < NT) { DMA_TILE(j + 3, (j + 3) & 3); } SBAR();
	v_mfma_f32_32x32x16_bf16 v[48:63], v[64:67], v[190:193], v[48:63]
	v_exp_f32_e32 v232, v96
	ds_read_b64_tr_b16 v[190:191], v176 offset:512
	ds_read_b64_tr_b16 v[192:193], v176 offset:2560
	s_waitcnt lgkmcnt(6)
	v_mfma_f32_32x32x16_bf16 v[48:63], v[68:71], v[194:197], v[48:63]
	v_exp_f32_e32 v233, v97
	ds_read_b64_tr_b16 v[194:195], v176 offset:4608
	ds_read_b64_tr_b16 v[196:197], v176 offset:6656
	s_waitcnt lgkmcnt(6)
	v_mfma_f32_32x32x16_bf16 v[48:63], v[72:75], v[200:203], v[48:63]
	v_exp_f32_e32 v234, v98
	ds_read_b64_tr_b16 v[200:201], v176 offset:8704
	ds_read_b64_tr_b16 v[202:203], v176 offset:10752
	ds_read_b64_tr_b16 v[208:209], v176 offset:12800
	ds_read_b64_tr_b16 v[210:211], v176 offset:14848
	s_waitcnt lgkmcnt(8)
	v_mfma_f32_32x32x16_bf16 v[48:63], v[76:79], v[204:207], v[48:63]
	v_exp_f32_e32 v235, v99
	s_waitcnt lgkmcnt(6)
	v_mfma_f32_32x32x16_bf16 v[32:47], v[64:67], v[190:193], v[32:47]
	v_exp_f32_e32 v236, v100
	ds_read_b64_tr_b16 v[190:191], v176 offset:1024
	ds_read_b64_tr_b16 v[192:193], v176 offset:3072
	s_waitcnt lgkmcnt(6)
	v_mfma_f32_32x32x16_bf16 v[32:47], v[68:71], v[194:197], v[32:47]
	v_exp_f32_e32 v237, v101
	ds_read_b64_tr_b16 v[194:195], v176 offset:5120
	ds_read_b64_tr_b16 v[196:197], v176 offset:7168
	s_waitcnt lgkmcnt(6)
	v_mfma_f32_32x32x16_bf16 v[32:47], v[72:75], v[200:203], v[32:47]
	v_exp_f32_e32 v238, v102
	ds_read_b64_tr_b16 v[200:201], v176 offset:9216
	ds_read_b64_tr_b16 v[202:203], v176 offset:11264
	ds_read_b64_tr_b16 v[204:205], v176 offset:13312
	ds_read_b64_tr_b16 v[206:207], v176 offset:15360
	s_waitcnt lgkmcnt(8)
	v_mfma_f32_32x32x16_bf16 v[32:47], v[76:79], v[208:211], v[32:47]
	v_exp_f32_e32 v239, v103
	v_exp_f32_e32 v240, v104
	s_waitcnt lgkmcnt(6)
	v_mfma_f32_32x32x16_bf16 v[16:31], v[64:67], v[190:193], v[16:31]
	v_exp_f32_e32 v241, v105
	ds_read_b64_tr_b16 v[190:191], v176 offset:1536
	ds_read_b64_tr_b16 v[192:193], v176 offset:3584
	s_waitcnt lgkmcnt(6)
	v_mfma_f32_32x32x16_bf16 v[16:31], v[68:71], v[194:197], v[16:31]
	v_exp_f32_e32 v242, v106
	ds_read_b64_tr_b16 v[194:195], v176 offset:5632
	ds_read_b64_tr_b16 v[196:197], v176 offset:7680
	s_waitcnt lgkmcnt(6)
	v_mfma_f32_32x32x16_bf16 v[16:31], v[72:75], v[200:203], v[16:31]
	v_exp_f32_e32 v243, v107
	ds_read_b64_tr_b16 v[200:201], v176 offset:9728
	ds_read_b64_tr_b16 v[202:203], v176 offset:11776
	ds_read_b64_tr_b16 v[208:209], v176 offset:13824
	ds_read_b64_tr_b16 v[210:211], v176 offset:15872
	s_waitcnt lgkmcnt(8)
	v_mfma_f32_32x32x16_bf16 v[16:31], v[76:79], v[204:207], v[16:31]
	v_exp_f32_e32 v244, v108
	s_waitcnt lgkmcnt(6)
	v_mfma_f32_32x32x16_bf16 v[0:15], v[64:67], v[190:193], v[0:15]
	v_exp_f32_e32 v245, v109
	s_waitcnt lgkmcnt(4)
	v_mfma_f32_32x32x16_bf16 v[0:15], v[68:71], v[194:197], v[0:15]
	v_exp_f32_e32 v246, v110
	s_waitcnt lgkmcnt(2)
	v_mfma_f32_32x32x16_bf16 v[0:15], v[72:75], v[200:203], v[0:15]
	v_exp_f32_e32 v247, v111
	s_waitcnt vmcnt(4)
	s_waitcnt lgkmcnt(0)
	s_barrier
	v_mfma_f32_32x32x16_bf16 v[0:15], v[76:79], v[208:211], v[0:15]
	s_and_b32 s40, s40, 0xc000
	s_add_i32 s40, s56, s40
	ds_read_b128 v[64:67], v178 offset:32768
	ds_read_b128 v[68:71], v178 offset:40960
	ds_read_b128 v[190:193], v179 offset:32768
	ds_read_b128 v[194:197], v179 offset:40960
	s_waitcnt lgkmcnt(3)
	v_mfma_f32_32x32x16_bf16 v[96:111], v[64:67], v[136:139], 0
	v_exp_f32_e32 v80, v80
	v_exp_f32_e32 v81, v81
	v_exp_f32_e32 v82, v82
	v_exp_f32_e32 v83, v83
	v_exp_f32_e32 v87, v87
	v_exp_f32_e32 v248, v93
	v_exp_f32_e32 v249, v94
	s_waitcnt lgkmcnt(2)
	v_mfma_f32_32x32x16_bf16 v[64:79], v[68:71], v[136:139], 0
	s_waitcnt lgkmcnt(1)
	v_mfma_f32_32x32x16_bf16 v[96:111], v[190:193], v[140:143], v[96:111]
	s_waitcnt lgkmcnt(0)
	v_mfma_f32_32x32x16_bf16 v[64:79], v[194:197], v[140:143], v[64:79]
	ds_read_b128 v[190:193], v180 offset:32768
	ds_read_b128 v[194:197], v180 offset:40960
	s_waitcnt lgkmcnt(1)
	v_mfma_f32_32x32x16_bf16 v[96:111], v[190:193], v[132:135], v[96:111]
	ds_read_b128 v[190:193], v181 offset:32768
	ds_read_b128 v[200:203], v181 offset:40960
	ds_read_b128 v[204:207], v182 offset:32768
	ds_read_b128 v[208:211], v182 offset:40960
	ds_read_b128 v[212:215], v183 offset:32768
	ds_read_b128 v[216:219], v183 offset:40960
	s_waitcnt lgkmcnt(6)
	v_mfma_f32_32x32x16_bf16 v[64:79], v[194:197], v[132:135], v[64:79]
	ds_read_b128 v[194:197], v184 offset:32768
	ds_read_b128 v[220:223], v184 offset:40960
	ds_read_b128 v[224:227], v185 offset:32768
	ds_read_b128 v[228:231], v185 offset:40960
	s_waitcnt lgkmcnt(9)
	v_mfma_f32_32x32x16_bf16 v[96:111], v[190:193], v[128:131], v[96:111]
	s_cmp_ge_u32 s72, s37
	s_cselect_b64 s[40:41], -1, 0
	s_and_b64 vcc, exec, s[40:41]
	s_cbranch_vccnz .LBB0_1367
	s_add_i32 s73, s66, s43
	s_add_u32 s98, s38, s26
	s_addc_u32 s99, s39, s27
	s_mov_b32 m0, s73
	s_add_i32 s43, s67, s43
	global_load_lds_dwordx4 v156, s[98:99]
	s_add_u32 s100, s38, s28
	s_addc_u32 s101, s39, s29
	s_add_i32 m0, s73, 0x2000
	s_nop 0
	global_load_lds_dwordx4 v158, s[98:99]
	s_mov_b32 m0, s43
	s_nop 0
	global_load_lds_dwordx4 v162, s[100:101]
	s_add_i32 m0, s43, 0x2000
	s_nop 0
	global_load_lds_dwordx4 v160, s[100:101]

; #define SBAR() __builtin_amdgcn_sched_barrier(0)
; #define PK4(P, BASE, OUT) do { u32x4 w = {cvtpk(P[BASE + 0], P[BASE + 1]), cvtpk(P[BASE + 2], P[BASE + 3]), cvtpk(P[BASE + 4], P[BASE + 5]), cvtpk(P[BASE + 6], P[BASE + 7])}; \
;     OUT = *reinterpret_cast<bf16x8*>(&w); } while (0)
; __device__ __forceinline__ void finishSM(f32x16& p0, f32x16& p1, float alpha, float& l_reg, bf16x8& pa0, bf16x8& pa1, bf16x8& pa2, bf16x8& pa3) {
;   for (int r = 0; r < 16; ++r) p1[r] = __builtin_amdgcn_exp2f(p1[r]);
;   float ps = 0; for (int r = 0; r < 16; ++r) ps += p0[r]; for (int r = 0; r < 16; ++r) ps += p1[r];
;   asm volatile("" : "+v"(ps));
;   l_reg = l_reg * alpha + ps;
;     ...
;   PK4(p0, 0, pa0); PK4(p0, 8, pa1); PK4(p1, 0, pa2); PK4(p1, 8, pa3);
;     ...
; }
; template <typename TQ> ...
;     ...
;     SBAR(); qkt(pB0, pB1, (const bf16*)(K_lds + (j & 3) * (int)SHM_K), qr, r32, hi);
;     finishSM(pA0, pA1, alA, l_reg, pa0, pa1, pa2, pa3); SBAR();
;     DMA_TILE(j + 2, (j + 2) & 3); SBAR();
;     pv_d0(o, vb0 + ((j - 1) & 3) * (int)SHM_V, pa0, pa1, pa2, pa3); partialSM<true>(pB0, pB1, m_reg, mnB, alB);
.Lat1365_b:
.Lat1365_b_in:
	s_mov_b32 s40, s33
	s_addk_i32 s33, 0xc000
	s_and_b32 s42, s33, 0xc000
	s_add_i32 s33, s56, s42
	ds_read_b128 v[80:83], v178 offset:49152
	ds_read_b128 v[84:87], v178 offset:57344
	ds_read_b128 v[198:201], v179 offset:49152
	ds_read_b128 v[202:205], v179 offset:57344
	s_waitcnt lgkmcnt(3)
	v_mfma_f32_32x32x16_bf16 v[96:111], v[80:83], v[136:139], 0
	v_exp_f32_e32 v238, v64
	v_add_f32_e32 v64, v197, v196
	v_add_f32_e32 v64, v193, v64
	v_add_f32_e32 v64, v195, v64
	s_waitcnt lgkmcnt(2)
	v_mfma_f32_32x32x16_bf16 v[80:95], v[84:87], v[136:139], 0
	v_add_f32_e32 v64, v191, v64
	v_add_f32_e32 v64, v194, v64
	v_add_f32_e32 v64, v190, v64
	v_add_f32_e32 v64, v192, v64
	v_add_f32_e32 v64, v169, v64
	v_add_f32_e32 v64, v171, v64
	s_waitcnt lgkmcnt(1)
	v_mfma_f32_32x32x16_bf16 v[96:111], v[198:201], v[140:143], v[96:111]
	v_add_f32_e32 v64, v167, v64
	v_add_f32_e32 v64, v170, v64
	v_add_f32_e32 v64, v165, v64
	v_add_f32_e32 v64, v168, v64
	v_add_f32_e32 v64, v164, v64
	v_add_f32_e32 v64, v166, v64
	v_exp_f32_e32 v239, v68
	s_waitcnt lgkmcnt(0)
	v_mfma_f32_32x32x16_bf16 v[80:95], v[202:205], v[140:143], v[80:95]
	ds_read_b128 v[198:201], v180 offset:49152
	ds_read_b128 v[202:205], v180 offset:57344
	v_add_f32_e32 v64, v238, v64
	v_exp_f32_e32 v240, v69
	v_exp_f32_e32 v241, v70
	v_exp_f32_e32 v242, v71
	s_waitcnt lgkmcnt(1)
	v_mfma_f32_32x32x16_bf16 v[96:111], v[198:201], v[132:135], v[96:111]
	ds_read_b128 v[198:201], v181 offset:49152
	ds_read_b128 v[206:209], v181 offset:57344
	ds_read_b128 v[210:213], v182 offset:49152
	ds_read_b128 v[214:217], v182 offset:57344
	ds_read_b128 v[218:221], v183 offset:49152
	ds_read_b128 v[222:225], v183 offset:57344
	v_exp_f32_e32 v243, v76
	v_exp_f32_e32 v244, v77
	v_exp_f32_e32 v245, v78
	v_exp_f32_e32 v79, v79
	s_waitcnt lgkmcnt(6)
	v_mfma_f32_32x32x16_bf16 v[80:95], v[202:205], v[132:135], v[80:95]
	ds_read_b128 v[202:205], v184 offset:49152
	ds_read_b128 v[226:229], v184 offset:57344
	ds_read_b128 v[230:233], v185 offset:49152
	ds_read_b128 v[234:237], v185 offset:57344
	s_waitcnt lgkmcnt(9)
	v_mfma_f32_32x32x16_bf16 v[96:111], v[198:201], v[128:131], v[96:111]
	v_exp_f32_e32 v199, v65
	v_exp_f32_e32 v200, v66
	v_exp_f32_e32 v201, v67
	v_add_f32_e32 v64, v199, v64
	v_add_f32_e32 v64, v200, v64
	v_add_f32_e32 v64, v201, v64
	s_waitcnt lgkmcnt(8)
	v_mfma_f32_32x32x16_bf16 v[80:95], v[206:209], v[128:131], v[80:95]
	v_exp_f32_e32 v206, v72
	v_add_f32_e32 v64, v239, v64
	v_exp_f32_e32 v207, v73
	v_add_f32_e32 v64, v240, v64
	v_exp_f32_e32 v208, v74
	v_add_f32_e32 v64, v241, v64
	v_exp_f32_e32 v209, v75
	s_waitcnt lgkmcnt(7)
	v_mfma_f32_32x32x16_bf16 v[96:111], v[210:213], v[124:127], v[96:111]
	v_add_f32_e32 v64, v242, v64
	v_add_f32_e32 v64, v206, v64
	v_add_f32_e32 v64, v207, v64
	v_add_f32_e32 v64, v208, v64
	v_add_f32_e32 v64, v209, v64
	v_add_f32_e32 v64, v243, v64
	v_add_f32_e32 v64, v244, v64
	s_waitcnt lgkmcnt(6)
	v_mfma_f32_32x32x16_bf16 v[80:95], v[214:217], v[124:127], v[80:95]
	v_add_f32_e32 v64, v245, v64
	v_add_f32_e32 v198, v79, v64
	v_cvt_pk_bf16_f32 v64, v196, v197
	v_cvt_pk_bf16_f32 v65, v193, v195
	v_cvt_pk_bf16_f32 v66, v191, v194
	v_cvt_pk_bf16_f32 v67, v190, v192
	s_waitcnt lgkmcnt(5)
	v_mfma_f32_32x32x16_bf16 v[96:111], v[218:221], v[120:123], v[96:111]
	v_cvt_pk_bf16_f32 v68, v169, v171
	v_cvt_pk_bf16_f32 v69, v167, v170
	v_cvt_pk_bf16_f32 v70, v165, v168
	v_cvt_pk_bf16_f32 v71, v164, v166
	v_cvt_pk_bf16_f32 v72, v238, v199
	v_cvt_pk_bf16_f32 v73, v200, v201
	v_cvt_pk_bf16_f32 v74, v239, v240
	s_waitcnt lgkmcnt(4)
	v_mfma_f32_32x32x16_bf16 v[80:95], v[222:225], v[120:123], v[80:95]
	v_cvt_pk_bf16_f32 v75, v241, v242
	v_cvt_pk_bf16_f32 v76, v206, v207
	v_cvt_pk_bf16_f32 v77, v208, v209
	v_cvt_pk_bf16_f32 v78, v243, v244
	v_cvt_pk_bf16_f32 v79, v245, v79
	s_waitcnt lgkmcnt(3)
	v_mfma_f32_32x32x16_bf16 v[96:111], v[202:205], v[116:119], v[96:111]
	s_add_i32 s33, s40, 0x8000
	s_and_b32 s43, s33, 0xc000
	ds_read_b64_tr_b16 v[190:191], v176 offset:32768
	ds_read_b64_tr_b16 v[192:193], v176 offset:34816
	ds_read_b64_tr_b16 v[194:195], v176 offset:36864
	ds_read_b64_tr_b16 v[196:197], v176 offset:38912
	s_waitcnt lgkmcnt(6)
	v_mfma_f32_32x32x16_bf16 v[80:95], v[226:229], v[116:119], v[80:95]
	ds_read_b64_tr_b16 v[200:201], v176 offset:40960
	ds_read_b64_tr_b16 v[202:203], v176 offset:43008
	ds_read_b64_tr_b16 v[204:205], v176 offset:45056
	ds_read_b64_tr_b16 v[206:207], v176 offset:47104
	s_add_i32 s73, s40, 0x4000
	s_and_b32 s73, s73, 0xc000
	s_add_u32 s98, s38, s22
	s_addc_u32 s99, s39, s23
	s_add_i32 s41, s66, s73
	s_add_u32 s100, s38, s24
	s_addc_u32 s101, s39, s25
	s_mov_b32 m0, s41
	s_add_i32 s73, s67, s73
	global_load_lds_dwordx4 v156, s[98:99]
	s_waitcnt lgkmcnt(9)
	v_mfma_f32_32x32x16_bf16 v[96:111], v[230:233], v[112:115], v[96:111]
	s_add_i32 m0, s41, 0x2000
	s_nop 0
	global_load_lds_dwordx4 v158, s[98:99]
	s_mov_b32 m0, s73
	s_nop 0
	global_load_lds_dwordx4 v162, s[100:101]
	s_waitcnt lgkmcnt(8)
; #define SBAR() __builtin_amdgcn_sched_barrier(0)
; #define PUBLISH(n) do { asm volatile("s_waitcnt vmcnt(" #n ")" ::: "memory"); asm volatile("s_waitcnt lgkmcnt(0)" ::: "memory"); __builtin_amdgcn_s_barrier(); SBAR(); } while (0)
; template <typename TQ> ...
;     ...
;     pv_d0(o, vb0 + ((j - 1) & 3) * (int)SHM_V, pa0, pa1, pa2, pa3); partialSM<true>(pB0, pB1, m_reg, mnB, alB);
;     PUBLISH(4);
;     SBAR(); qkt(pA0, pA1, (const bf16*)(K_lds + ((j + 1) & 3) * (int)SHM_K), qr, r32, hi);
;     finishSM(pB0, pB1, alB, l_reg, pa0, pa1, pa2, pa3); SBAR();
;     if (j + 3 < NT) { DMA_TILE(j + 3, (j + 3) & 3); } SBAR();
	v_mfma_f32_32x32x16_bf16 v[80:95], v[234:237], v[112:115], v[80:95]
	s_add_i32 m0, s73, 0x2000
	s_nop 0
	global_load_lds_dwordx4 v160, s[100:101]
	s_nop 0
	s_waitcnt lgkmcnt(6)
	v_mfma_f32_32x32x16_bf16 v[48:63], v[64:67], v[190:193], v[48:63]
	v_exp_f32_e32 v232, v96
	ds_read_b64_tr_b16 v[190:191], v176 offset:33280
	ds_read_b64_tr_b16 v[192:193], v176 offset:35328
	s_waitcnt lgkmcnt(6)
	v_mfma_f32_32x32x16_bf16 v[48:63], v[68:71], v[194:197], v[48:63]
	v_exp_f32_e32 v233, v97
	ds_read_b64_tr_b16 v[194:195], v176 offset:37376
	ds_read_b64_tr_b16 v[196:197], v176 offset:39424
	s_waitcnt lgkmcnt(6)
	v_mfma_f32_32x32x16_bf16 v[48:63], v[72:75], v[200:203], v[48:63]
	v_exp_f32_e32 v234, v98
	ds_read_b64_tr_b16 v[200:201], v176 offset:41472
	ds_read_b64_tr_b16 v[202:203], v176 offset:43520
	ds_read_b64_tr_b16 v[208:209], v176 offset:45568
	ds_read_b64_tr_b16 v[210:211], v176 offset:47616
	s_waitcnt lgkmcnt(8)
	v_mfma_f32_32x32x16_bf16 v[48:63], v[76:79], v[204:207], v[48:63]
	v_exp_f32_e32 v235, v99
	s_waitcnt lgkmcnt(6)
	v_mfma_f32_32x32x16_bf16 v[32:47], v[64:67], v[190:193], v[32:47]
	v_exp_f32_e32 v236, v100
	ds_read_b64_tr_b16 v[190:191], v176 offset:33792
	ds_read_b64_tr_b16 v[192:193], v176 offset:35840
	s_waitcnt lgkmcnt(6)
	v_mfma_f32_32x32x16_bf16 v[32:47], v[68:71], v[194:197], v[32:47]
	v_exp_f32_e32 v237, v101
	ds_read_b64_tr_b16 v[194:195], v176 offset:37888
	ds_read_b64_tr_b16 v[196:197], v176 offset:39936
	s_waitcnt lgkmcnt(6)
	v_mfma_f32_32x32x16_bf16 v[32:47], v[72:75], v[200:203], v[32:47]
	v_exp_f32_e32 v238, v102
	ds_read_b64_tr_b16 v[200:201], v176 offset:41984
	ds_read_b64_tr_b16 v[202:203], v176 offset:44032
	ds_read_b64_tr_b16 v[204:205], v176 offset:46080
	ds_read_b64_tr_b16 v[206:207], v176 offset:48128
	s_waitcnt lgkmcnt(8)
	v_mfma_f32_32x32x16_bf16 v[32:47], v[76:79], v[208:211], v[32:47]
	v_exp_f32_e32 v239, v103
	v_exp_f32_e32 v240, v104
	s_waitcnt lgkmcnt(6)
	v_mfma_f32_32x32x16_bf16 v[16:31], v[64:67], v[190:193], v[16:31]
	v_exp_f32_e32 v241, v105
	ds_read_b64_tr_b16 v[190:191], v176 offset:34304
	ds_read_b64_tr_b16 v[192:193], v176 offset:36352
	s_waitcnt lgkmcnt(6)
	v_mfma_f32_32x32x16_bf16 v[16:31], v[68:71], v[194:197], v[16:31]
	v_exp_f32_e32 v242, v106
	ds_read_b64_tr_b16 v[194:195], v176 offset:38400
	ds_read_b64_tr_b16 v[196:197], v176 offset:40448
	s_waitcnt lgkmcnt(6)
	v_mfma_f32_32x32x16_bf16 v[16:31], v[72:75], v[200:203], v[16:31]
	v_exp_f32_e32 v243, v107
	ds_read_b64_tr_b16 v[200:201], v176 offset:42496
	ds_read_b64_tr_b16 v[202:203], v176 offset:44544
	ds_read_b64_tr_b16 v[208:209], v176 offset:46592
	ds_read_b64_tr_b16 v[210:211], v176 offset:48640
	s_waitcnt lgkmcnt(8)
	v_mfma_f32_32x32x16_bf16 v[16:31], v[76:79], v[204:207], v[16:31]
	v_exp_f32_e32 v244, v108
	s_waitcnt lgkmcnt(6)
	v_mfma_f32_32x32x16_bf16 v[0:15], v[64:67], v[190:193], v[0:15]
	v_exp_f32_e32 v245, v109
	s_waitcnt lgkmcnt(4)
	v_mfma_f32_32x32x16_bf16 v[0:15], v[68:71], v[194:197], v[0:15]
	v_exp_f32_e32 v246, v110
	s_waitcnt lgkmcnt(2)
	v_mfma_f32_32x32x16_bf16 v[0:15], v[72:75], v[200:203], v[0:15]
	v_exp_f32_e32 v247, v111
	s_waitcnt vmcnt(4)
	s_waitcnt lgkmcnt(0)
	s_barrier
	v_mfma_f32_32x32x16_bf16 v[0:15], v[76:79], v[208:211], v[0:15]
	s_and_b32 s40, s40, 0xc000
	s_add_i32 s40, s56, s40
	ds_read_b128 v[64:67], v178
	ds_read_b128 v[68:71], v178 offset:8192
	ds_read_b128 v[190:193], v179
	ds_read_b128 v[194:197], v179 offset:8192
	s_waitcnt lgkmcnt(3)
	v_mfma_f32_32x32x16_bf16 v[96:111], v[64:67], v[136:139], 0
	v_exp_f32_e32 v80, v80
	v_exp_f32_e32 v81, v81
	v_exp_f32_e32 v82, v82
	v_exp_f32_e32 v83, v83
	v_exp_f32_e32 v87, v87
	v_exp_f32_e32 v248, v93
	v_exp_f32_e32 v249, v94
	s_waitcnt lgkmcnt(2)
	v_mfma_f32_32x32x16_bf16 v[64:79], v[68:71], v[136:139], 0
	s_waitcnt lgkmcnt(1)
	v_mfma_f32_32x32x16_bf16 v[96:111], v[190:193], v[140:143], v[96:111]
	s_waitcnt lgkmcnt(0)
	v_mfma_f32_32x32x16_bf16 v[64:79], v[194:197], v[140:143], v[64:79]
	ds_read_b128 v[190:193], v180
	ds_read_b128 v[194:197], v180 offset:8192
	s_waitcnt lgkmcnt(1)
	v_mfma_f32_32x32x16_bf16 v[96:111], v[190:193], v[132:135], v[96:111]
	ds_read_b128 v[190:193], v181
	ds_read_b128 v[200:203], v181 offset:8192
	ds_read_b128 v[204:207], v182
	ds_read_b128 v[208:211], v182 offset:8192
	ds_read_b128 v[212:215], v183
	ds_read_b128 v[216:219], v183 offset:8192
	s_waitcnt lgkmcnt(6)
	v_mfma_f32_32x32x16_bf16 v[64:79], v[194:197], v[132:135], v[64:79]
	ds_read_b128 v[194:197], v184
	ds_read_b128 v[220:223], v184 offset:8192
	ds_read_b128 v[224:227], v185
	ds_read_b128 v[228:231], v185 offset:8192
	s_waitcnt lgkmcnt(9)
	v_mfma_f32_32x32x16_bf16 v[96:111], v[190:193], v[128:131], v[96:111]
	s_cmp_ge_u32 s72, s37
	s_cselect_b64 s[40:41], -1, 0
	s_and_b64 vcc, exec, s[40:41]
	s_cbranch_vccnz .Lat1367_b

; #define SBAR() __builtin_amdgcn_sched_barrier(0)
; template <typename TQ> ...
;     ...
;     if (j + 3 < NT) { DMA_TILE(j + 3, (j + 3) & 3); } SBAR();
	s_add_i32 s73, s66, s43
	s_add_u32 s98, s38, s26
	s_addc_u32 s99, s39, s27
	s_mov_b32 m0, s73
	s_add_i32 s43, s67, s43
	global_load_lds_dwordx4 v156, s[98:99]
	s_add_u32 s100, s38, s28
	s_addc_u32 s101, s39, s29
	s_add_i32 m0, s73, 0x2000
	s_nop 0
	global_load_lds_dwordx4 v158, s[98:99]
	s_mov_b32 m0, s43
	s_nop 0
	global_load_lds_dwordx4 v162, s[100:101]
	s_add_i32 m0, s43, 0x2000
	s_nop 0
	global_load_lds_dwordx4 v160, s[100:101]
